# P5 K-loop: the dead 's_setprio 0; s_setprio 1' pair between the two MFMA blocks of each compute segment removed; rest as best
# baseline (speedup 1.0000x reference)
.LBB0_507:
	ds_read_b128 v[166:169], v163
	ds_read_b128 v[170:173], v163 offset:1024
	ds_read_b128 v[174:177], v163 offset:2048
	ds_read_b128 v[178:181], v163 offset:3072
	ds_read_b128 v[182:185], v164
	ds_read_b128 v[188:191], v164 offset:1024
	ds_read_b128 v[192:195], v164 offset:2048
	ds_read_b128 v[196:199], v164 offset:3072
	s_add_u32 s44, s42, 0xfff80080
	s_addc_u32 s45, s43, -1
	s_cmp_eq_u32 s52, 28
	s_cselect_b32 s47, s7, s45
	s_cselect_b32 s46, s6, s44
	s_cselect_b32 s45, s23, s21
	s_cselect_b32 s44, s22, s17
	s_mov_b32 m0, s94
	v_lshl_add_u64 v[232:233], s[42:43], 0, v[152:153]
	ds_read_b128 v[200:203], v165
	ds_read_b128 v[204:207], v165 offset:1024
	ds_read_b128 v[208:211], v165 offset:2048
	ds_read_b128 v[212:215], v165 offset:3072
	ds_read_b128 v[216:219], v165 offset:4096
	ds_read_b128 v[220:223], v165 offset:5120
	ds_read_b128 v[224:227], v165 offset:6144
	ds_read_b128 v[228:231], v165 offset:7168
	global_load_lds_dwordx4 v[232:233], off
	v_lshl_add_u64 v[232:233], s[42:43], 0, v[154:155]
	s_mov_b32 m0, s95
	s_nop 0
	global_load_lds_dwordx4 v[232:233], off
	s_waitcnt vmcnt(8)
	s_waitcnt lgkmcnt(0)
	s_barrier
	s_setprio 1
	s_waitcnt lgkmcnt(0)
	v_mfma_f32_16x16x32_bf16 v[124:127], v[166:169], v[200:203], v[124:127]
	v_mfma_f32_16x16x32_bf16 v[120:123], v[174:177], v[200:203], v[120:123]
	v_mfma_f32_16x16x32_bf16 v[108:111], v[166:169], v[208:211], v[108:111]
	v_mfma_f32_16x16x32_bf16 v[104:107], v[174:177], v[208:211], v[104:107]
	v_mfma_f32_16x16x32_bf16 v[92:95], v[166:169], v[216:219], v[92:95]
	v_mfma_f32_16x16x32_bf16 v[88:91], v[174:177], v[216:219], v[88:91]
	v_mfma_f32_16x16x32_bf16 v[76:79], v[166:169], v[224:227], v[76:79]
	v_mfma_f32_16x16x32_bf16 v[72:75], v[174:177], v[224:227], v[72:75]
	v_mfma_f32_16x16x32_bf16 v[124:127], v[170:173], v[204:207], v[124:127]
	v_mfma_f32_16x16x32_bf16 v[120:123], v[178:181], v[204:207], v[120:123]
	v_mfma_f32_16x16x32_bf16 v[108:111], v[170:173], v[212:215], v[108:111]
	v_mfma_f32_16x16x32_bf16 v[104:107], v[178:181], v[212:215], v[104:107]
	v_mfma_f32_16x16x32_bf16 v[92:95], v[170:173], v[220:223], v[92:95]
	v_mfma_f32_16x16x32_bf16 v[88:91], v[178:181], v[220:223], v[88:91]
	v_mfma_f32_16x16x32_bf16 v[76:79], v[170:173], v[228:231], v[76:79]
	v_mfma_f32_16x16x32_bf16 v[72:75], v[178:181], v[228:231], v[72:75]
	v_mfma_f32_16x16x32_bf16 v[116:119], v[182:185], v[200:203], v[116:119]
	v_mfma_f32_16x16x32_bf16 v[112:115], v[192:195], v[200:203], v[112:115]
	v_mfma_f32_16x16x32_bf16 v[100:103], v[182:185], v[208:211], v[100:103]
	v_mfma_f32_16x16x32_bf16 v[96:99], v[192:195], v[208:211], v[96:99]
	v_mfma_f32_16x16x32_bf16 v[84:87], v[182:185], v[216:219], v[84:87]
	v_mfma_f32_16x16x32_bf16 v[80:83], v[192:195], v[216:219], v[80:83]
	v_mfma_f32_16x16x32_bf16 v[68:71], v[182:185], v[224:227], v[68:71]
	v_mfma_f32_16x16x32_bf16 v[64:67], v[192:195], v[224:227], v[64:67]
	v_mfma_f32_16x16x32_bf16 v[116:119], v[188:191], v[204:207], v[116:119]
	v_mfma_f32_16x16x32_bf16 v[112:115], v[196:199], v[204:207], v[112:115]
	v_mfma_f32_16x16x32_bf16 v[100:103], v[188:191], v[212:215], v[100:103]
	v_mfma_f32_16x16x32_bf16 v[96:99], v[196:199], v[212:215], v[96:99]
	v_mfma_f32_16x16x32_bf16 v[84:87], v[188:191], v[220:223], v[84:87]
	v_mfma_f32_16x16x32_bf16 v[80:83], v[196:199], v[220:223], v[80:83]
	v_mfma_f32_16x16x32_bf16 v[68:71], v[188:191], v[228:231], v[68:71]
	v_mfma_f32_16x16x32_bf16 v[64:67], v[196:199], v[228:231], v[64:67]
	s_setprio 0
	s_barrier
	s_mov_b32 m0, s96
	v_lshl_add_u64 v[232:233], s[44:45], 0, v[130:131]
	s_add_u32 s54, s44, 0x80000
	ds_read_b128 v[200:203], v165 offset:16384
	ds_read_b128 v[204:207], v165 offset:17408
	ds_read_b128 v[208:211], v165 offset:18432
	ds_read_b128 v[212:215], v165 offset:19456
	ds_read_b128 v[216:219], v165 offset:20480
	ds_read_b128 v[220:223], v165 offset:21504
	ds_read_b128 v[224:227], v165 offset:22528
	ds_read_b128 v[228:231], v165 offset:23552
	global_load_lds_dwordx4 v[232:233], off
	v_lshl_add_u64 v[234:235], s[44:45], 0, v[134:135]
	s_mov_b32 m0, s97
	s_addc_u32 s55, s45, 0
	global_load_lds_dwordx4 v[234:235], off
	v_lshl_add_u64 v[236:237], s[54:55], 0, v[130:131]
	s_mov_b32 m0, s91
	v_lshl_add_u64 v[238:239], s[46:47], 0, v[132:133]
	global_load_lds_dwordx4 v[236:237], off
	v_lshl_add_u64 v[236:237], s[54:55], 0, v[134:135]
	s_mov_b32 m0, s26
	s_nop 0
	global_load_lds_dwordx4 v[236:237], off
	v_lshl_add_u64 v[236:237], s[46:47], 0, v[128:129]
	s_mov_b32 m0, s33
	s_nop 0
	global_load_lds_dwordx4 v[236:237], off
	s_mov_b32 m0, s88
	s_nop 0
	global_load_lds_dwordx4 v[238:239], off
	s_waitcnt vmcnt(8)
	s_waitcnt lgkmcnt(0)
	s_barrier
	s_setprio 1
	s_waitcnt lgkmcnt(0)
	v_mfma_f32_16x16x32_bf16 v[60:63], v[166:169], v[200:203], v[60:63]
	v_mfma_f32_16x16x32_bf16 v[56:59], v[174:177], v[200:203], v[56:59]
	v_mfma_f32_16x16x32_bf16 v[44:47], v[166:169], v[208:211], v[44:47]
	v_mfma_f32_16x16x32_bf16 v[40:43], v[174:177], v[208:211], v[40:43]
	v_mfma_f32_16x16x32_bf16 v[28:31], v[166:169], v[216:219], v[28:31]
	v_mfma_f32_16x16x32_bf16 v[24:27], v[174:177], v[216:219], v[24:27]
	v_mfma_f32_16x16x32_bf16 v[12:15], v[166:169], v[224:227], v[12:15]
	v_mfma_f32_16x16x32_bf16 v[8:11], v[174:177], v[224:227], v[8:11]
	v_mfma_f32_16x16x32_bf16 v[60:63], v[170:173], v[204:207], v[60:63]
	v_mfma_f32_16x16x32_bf16 v[56:59], v[178:181], v[204:207], v[56:59]
	v_mfma_f32_16x16x32_bf16 v[44:47], v[170:173], v[212:215], v[44:47]
	v_mfma_f32_16x16x32_bf16 v[40:43], v[178:181], v[212:215], v[40:43]
	v_mfma_f32_16x16x32_bf16 v[28:31], v[170:173], v[220:223], v[28:31]
	v_mfma_f32_16x16x32_bf16 v[24:27], v[178:181], v[220:223], v[24:27]
	v_mfma_f32_16x16x32_bf16 v[12:15], v[170:173], v[228:231], v[12:15]
	v_mfma_f32_16x16x32_bf16 v[8:11], v[178:181], v[228:231], v[8:11]
	v_mfma_f32_16x16x32_bf16 v[52:55], v[182:185], v[200:203], v[52:55]
	v_mfma_f32_16x16x32_bf16 v[48:51], v[192:195], v[200:203], v[48:51]
	v_mfma_f32_16x16x32_bf16 v[36:39], v[182:185], v[208:211], v[36:39]
	v_mfma_f32_16x16x32_bf16 v[32:35], v[192:195], v[208:211], v[32:35]
	v_mfma_f32_16x16x32_bf16 v[20:23], v[182:185], v[216:219], v[20:23]
	v_mfma_f32_16x16x32_bf16 v[16:19], v[192:195], v[216:219], v[16:19]
	v_mfma_f32_16x16x32_bf16 v[4:7], v[182:185], v[224:227], v[4:7]
	v_mfma_f32_16x16x32_bf16 v[0:3], v[192:195], v[224:227], v[0:3]
	v_mfma_f32_16x16x32_bf16 v[52:55], v[188:191], v[204:207], v[52:55]
	v_mfma_f32_16x16x32_bf16 v[48:51], v[196:199], v[204:207], v[48:51]
	v_mfma_f32_16x16x32_bf16 v[36:39], v[188:191], v[212:215], v[36:39]
	v_mfma_f32_16x16x32_bf16 v[32:35], v[196:199], v[212:215], v[32:35]
	v_mfma_f32_16x16x32_bf16 v[20:23], v[188:191], v[220:223], v[20:23]
	v_mfma_f32_16x16x32_bf16 v[16:19], v[196:199], v[220:223], v[16:19]
	v_mfma_f32_16x16x32_bf16 v[4:7], v[188:191], v[228:231], v[4:7]
	v_mfma_f32_16x16x32_bf16 v[0:3], v[196:199], v[228:231], v[0:3]
	s_setprio 0
	s_barrier
	v_add_u32_e32 v178, s29, v162
	v_add_u32_e32 v187, s41, v162
	ds_read_b128 v[166:169], v178
	ds_read_b128 v[170:173], v178 offset:1024
	ds_read_b128 v[174:177], v178 offset:2048
	ds_read_b128 v[178:181], v178 offset:3072
	ds_read_b128 v[182:185], v187
	ds_read_b128 v[188:191], v187 offset:1024
	ds_read_b128 v[192:195], v187 offset:2048
	ds_read_b128 v[196:199], v187 offset:3072
	s_add_u32 s46, s46, 0x80000
	s_addc_u32 s47, s47, 0
	s_mov_b32 m0, s89
	v_lshl_add_u64 v[240:241], s[46:47], 0, v[128:129]
	ds_read_b128 v[200:203], v165 offset:32768
	ds_read_b128 v[204:207], v165 offset:33792
	ds_read_b128 v[208:211], v165 offset:34816
	ds_read_b128 v[212:215], v165 offset:35840
	ds_read_b128 v[216:219], v165 offset:36864
	ds_read_b128 v[220:223], v165 offset:37888
	ds_read_b128 v[224:227], v165 offset:38912
	ds_read_b128 v[228:231], v165 offset:39936
	global_load_lds_dwordx4 v[240:241], off
	v_lshl_add_u64 v[240:241], s[46:47], 0, v[132:133]
	s_mov_b32 m0, s90
	s_nop 0
	global_load_lds_dwordx4 v[240:241], off
	s_waitcnt vmcnt(8)
	s_waitcnt lgkmcnt(0)
	s_barrier
	s_setprio 1
	s_waitcnt lgkmcnt(0)
	v_mfma_f32_16x16x32_bf16 v[124:127], v[166:169], v[200:203], v[124:127]
	v_mfma_f32_16x16x32_bf16 v[120:123], v[174:177], v[200:203], v[120:123]
	v_mfma_f32_16x16x32_bf16 v[108:111], v[166:169], v[208:211], v[108:111]
	v_mfma_f32_16x16x32_bf16 v[104:107], v[174:177], v[208:211], v[104:107]
	v_mfma_f32_16x16x32_bf16 v[92:95], v[166:169], v[216:219], v[92:95]
	v_mfma_f32_16x16x32_bf16 v[88:91], v[174:177], v[216:219], v[88:91]
	v_mfma_f32_16x16x32_bf16 v[76:79], v[166:169], v[224:227], v[76:79]
	v_mfma_f32_16x16x32_bf16 v[72:75], v[174:177], v[224:227], v[72:75]
	v_mfma_f32_16x16x32_bf16 v[124:127], v[170:173], v[204:207], v[124:127]
	v_mfma_f32_16x16x32_bf16 v[120:123], v[178:181], v[204:207], v[120:123]
	v_mfma_f32_16x16x32_bf16 v[108:111], v[170:173], v[212:215], v[108:111]
	v_mfma_f32_16x16x32_bf16 v[104:107], v[178:181], v[212:215], v[104:107]
	v_mfma_f32_16x16x32_bf16 v[92:95], v[170:173], v[220:223], v[92:95]
	v_mfma_f32_16x16x32_bf16 v[88:91], v[178:181], v[220:223], v[88:91]
	v_mfma_f32_16x16x32_bf16 v[76:79], v[170:173], v[228:231], v[76:79]
	v_mfma_f32_16x16x32_bf16 v[72:75], v[178:181], v[228:231], v[72:75]
	v_mfma_f32_16x16x32_bf16 v[116:119], v[182:185], v[200:203], v[116:119]
	v_mfma_f32_16x16x32_bf16 v[112:115], v[192:195], v[200:203], v[112:115]
	v_mfma_f32_16x16x32_bf16 v[100:103], v[182:185], v[208:211], v[100:103]
	v_mfma_f32_16x16x32_bf16 v[96:99], v[192:195], v[208:211], v[96:99]
	v_mfma_f32_16x16x32_bf16 v[84:87], v[182:185], v[216:219], v[84:87]
	v_mfma_f32_16x16x32_bf16 v[80:83], v[192:195], v[216:219], v[80:83]
	v_mfma_f32_16x16x32_bf16 v[68:71], v[182:185], v[224:227], v[68:71]
	v_mfma_f32_16x16x32_bf16 v[64:67], v[192:195], v[224:227], v[64:67]
	v_mfma_f32_16x16x32_bf16 v[116:119], v[188:191], v[204:207], v[116:119]
	v_mfma_f32_16x16x32_bf16 v[112:115], v[196:199], v[204:207], v[112:115]
	v_mfma_f32_16x16x32_bf16 v[100:103], v[188:191], v[212:215], v[100:103]
	v_mfma_f32_16x16x32_bf16 v[96:99], v[196:199], v[212:215], v[96:99]
	v_mfma_f32_16x16x32_bf16 v[84:87], v[188:191], v[220:223], v[84:87]
	v_mfma_f32_16x16x32_bf16 v[80:83], v[196:199], v[220:223], v[80:83]
	v_mfma_f32_16x16x32_bf16 v[68:71], v[188:191], v[228:231], v[68:71]
	v_mfma_f32_16x16x32_bf16 v[64:67], v[196:199], v[228:231], v[64:67]
	s_setprio 0
	s_barrier
	s_mov_b32 m0, s27
	v_lshl_add_u64 v[232:233], v[232:233], 0, s[14:15]
	s_add_u32 s44, s44, 0x80080
	ds_read_b128 v[200:203], v165 offset:49152
	ds_read_b128 v[204:207], v165 offset:50176
	ds_read_b128 v[208:211], v165 offset:51200
	ds_read_b128 v[212:215], v165 offset:52224
	ds_read_b128 v[216:219], v165 offset:53248
	ds_read_b128 v[220:223], v165 offset:54272
	ds_read_b128 v[224:227], v165 offset:55296
	ds_read_b128 v[228:231], v165 offset:56320
	global_load_lds_dwordx4 v[232:233], off
	v_lshl_add_u64 v[232:233], v[234:235], 0, s[14:15]
	s_mov_b32 m0, s34
	s_addc_u32 s45, s45, 0
	global_load_lds_dwordx4 v[232:233], off
	v_lshl_add_u64 v[232:233], s[44:45], 0, v[130:131]
	s_mov_b32 m0, s35
	s_nop 0
	global_load_lds_dwordx4 v[232:233], off
	v_lshl_add_u64 v[232:233], s[44:45], 0, v[134:135]
	s_mov_b32 m0, s28
	s_nop 0
	global_load_lds_dwordx4 v[232:233], off
	v_lshl_add_u64 v[232:233], v[236:237], 0, s[14:15]
	s_mov_b32 m0, s92
	s_nop 0
	global_load_lds_dwordx4 v[232:233], off
	v_lshl_add_u64 v[232:233], v[238:239], 0, s[14:15]
	s_mov_b32 m0, s93
	s_nop 0
	global_load_lds_dwordx4 v[232:233], off
	s_waitcnt vmcnt(8)
	s_waitcnt lgkmcnt(0)
	s_barrier
	s_setprio 1
	s_waitcnt lgkmcnt(0)
	v_mfma_f32_16x16x32_bf16 v[60:63], v[166:169], v[200:203], v[60:63]
	v_mfma_f32_16x16x32_bf16 v[56:59], v[174:177], v[200:203], v[56:59]
	v_mfma_f32_16x16x32_bf16 v[44:47], v[166:169], v[208:211], v[44:47]
	v_mfma_f32_16x16x32_bf16 v[40:43], v[174:177], v[208:211], v[40:43]
	v_mfma_f32_16x16x32_bf16 v[28:31], v[166:169], v[216:219], v[28:31]
	v_mfma_f32_16x16x32_bf16 v[24:27], v[174:177], v[216:219], v[24:27]
	v_mfma_f32_16x16x32_bf16 v[12:15], v[166:169], v[224:227], v[12:15]
	v_mfma_f32_16x16x32_bf16 v[8:11], v[174:177], v[224:227], v[8:11]
	v_mfma_f32_16x16x32_bf16 v[60:63], v[170:173], v[204:207], v[60:63]
	v_mfma_f32_16x16x32_bf16 v[56:59], v[178:181], v[204:207], v[56:59]
	v_mfma_f32_16x16x32_bf16 v[44:47], v[170:173], v[212:215], v[44:47]
	v_mfma_f32_16x16x32_bf16 v[40:43], v[178:181], v[212:215], v[40:43]
	v_mfma_f32_16x16x32_bf16 v[28:31], v[170:173], v[220:223], v[28:31]
	v_mfma_f32_16x16x32_bf16 v[24:27], v[178:181], v[220:223], v[24:27]
	v_mfma_f32_16x16x32_bf16 v[12:15], v[170:173], v[228:231], v[12:15]
	v_mfma_f32_16x16x32_bf16 v[8:11], v[178:181], v[228:231], v[8:11]
	v_mfma_f32_16x16x32_bf16 v[52:55], v[182:185], v[200:203], v[52:55]
	v_mfma_f32_16x16x32_bf16 v[48:51], v[192:195], v[200:203], v[48:51]
	v_mfma_f32_16x16x32_bf16 v[36:39], v[182:185], v[208:211], v[36:39]
	v_mfma_f32_16x16x32_bf16 v[32:35], v[192:195], v[208:211], v[32:35]
	v_mfma_f32_16x16x32_bf16 v[20:23], v[182:185], v[216:219], v[20:23]
	v_mfma_f32_16x16x32_bf16 v[16:19], v[192:195], v[216:219], v[16:19]
	v_mfma_f32_16x16x32_bf16 v[4:7], v[182:185], v[224:227], v[4:7]
	v_mfma_f32_16x16x32_bf16 v[0:3], v[192:195], v[224:227], v[0:3]
	v_mfma_f32_16x16x32_bf16 v[52:55], v[188:191], v[204:207], v[52:55]
	v_mfma_f32_16x16x32_bf16 v[48:51], v[196:199], v[204:207], v[48:51]
	v_mfma_f32_16x16x32_bf16 v[36:39], v[188:191], v[212:215], v[36:39]
	v_mfma_f32_16x16x32_bf16 v[32:35], v[196:199], v[212:215], v[32:35]
	v_mfma_f32_16x16x32_bf16 v[20:23], v[188:191], v[220:223], v[20:23]
	v_mfma_f32_16x16x32_bf16 v[16:19], v[196:199], v[220:223], v[16:19]
	v_mfma_f32_16x16x32_bf16 v[4:7], v[188:191], v[228:231], v[4:7]
	v_mfma_f32_16x16x32_bf16 v[0:3], v[196:199], v[228:231], v[0:3]
	s_setprio 0
	s_barrier
	s_add_i32 s52, s52, 2
	s_add_u32 s42, s42, 0x100
	s_addc_u32 s43, s43, 0
	s_add_u32 s17, s17, 0x100
	s_addc_u32 s21, s21, 0
	s_cmp_gt_u32 s52, 29
	s_cbranch_scc0 .LBB0_507
	s_and_b64 vcc, exec, s[78:79]
	s_cbranch_vccz .LBB0_510
	s_barrier
